# 64-byte alignment of the LDS-DMA GEMM loop branch targets (stage0 back-edge target and the per-stage join labels)
# speedup vs baseline: 1.0024x; 1.0024x over previous
; DI int TIDX() { int t = threadIdx.x; asm volatile("" : "+v"(t)); return t; }
; #define XCD_LOOP(Mx, ntn) const int xcd_ = BIDX() & 7; for (int u_ = BIDX() >> 3; u_ < (Mx) * (ntn); u_ += (int)(gridDim.x >> 3))
; DI void gemm_tile_deep(const h16* __restrict__ A, int lda, const h16* __restrict__ B, int ldb, int K, f32x16 (&acc)[2][2], h16* sm) {
;   const int tid = TIDX(), lane = tid & 63, w = tid >> 6, wm = w >> 1, wn = w & 1, r = lane & 31, hh = lane >> 5;
;   const unsigned ao = (unsigned)(tid >> 3) * (unsigned)lda + (unsigned)(tid & 7) * 8u;
;   const unsigned bo = (unsigned)(tid >> 3) * (unsigned)ldb + (unsigned)(tid & 7) * 8u;
;   const h16* ag = A;
;   const h16* bg = B;
;   u32x4 ra0[4], rb0[4], ra1[4], rb1[4];
; #pragma unroll
;   for (int i = 0; i < 4; ++i) {
;     ra0[i] = *(const u32x4*)(ag + (ao + (unsigned)i * 32u * (unsigned)lda));
;     rb0[i] = *(const u32x4*)(bg + (bo + (unsigned)i * 32u * (unsigned)ldb));
;   }
;   ag += 64; bg += 64;
; #pragma unroll
;   for (int i = 0; i < 4; ++i) {
;     ra1[i] = *(const u32x4*)(ag + (ao + (unsigned)i * 32u * (unsigned)lda));
;     rb1[i] = *(const u32x4*)(bg + (bo + (unsigned)i * 32u * (unsigned)ldb));
;   }
;   const int nk = K >> 6;
;   const int wofs = (tid >> 3) * LSTR + (tid & 7) * 8;
; DI void phase_gemm_plain(const h16* A, int lda, const h16* Bt, int K, h16* C, int ldc, int mt0, int mt1, int ntn, char* smem) {
;     ...
;   XCD_LOOP(Mx, ntn) {
;     int mt_, nt_;
;     tile_map(u_, Mx, ntn, xcd_, mt_, nt_);
;     const int m0 = (mt0 + mt_) * 128, n0 = nt_ * 128;
;     f32x16 acc[2][2];
;     zero_acc(acc);
;     gemm_tile_deep(A + (size_t)m0 * lda, lda, Bt + (size_t)n0 * K, K, K, acc, (h16*)smem);
.LBB0_58:
	s_ashr_i32 s8, s15, 31
	s_lshr_b32 s8, s8, 26
	s_add_i32 s8, s15, s8
	s_ashr_i32 s9, s8, 6
	s_lshl_b32 s9, s9, 3
	s_sub_i32 s10, s20, s9
	s_min_i32 s10, s10, 8
	s_abs_i32 s11, s10
	v_cvt_f32_u32_e32 v0, s11
	s_sub_i32 s23, 0, s11
	s_andn2_b32 s8, s8, 63
	s_sub_i32 s8, s15, s8
	v_rcp_iflag_f32_e32 v0, v0
	s_abs_i32 s12, s8
	s_xor_b32 s13, s8, s10
	s_ashr_i32 s13, s13, 31
	v_mul_f32_e32 v0, 0x4f7ffffe, v0
	v_cvt_u32_f32_e32 v0, v0
	v_mov_b32_e32 v18, v203
	v_mov_b32_e32 v7, v1
	v_readfirstlane_b32 s24, v0
	s_mul_i32 s23, s23, s24
	s_mul_hi_u32 s23, s24, s23
	s_add_i32 s24, s24, s23
	s_mul_hi_u32 s23, s12, s24
	s_mul_i32 s24, s23, s11
	s_sub_i32 s12, s12, s24
	s_add_i32 s25, s23, 1
	s_sub_i32 s24, s12, s11
	s_cmp_ge_u32 s12, s11
	s_cselect_b32 s23, s25, s23
	s_cselect_b32 s12, s24, s12
	s_add_i32 s24, s23, 1
	s_cmp_ge_u32 s12, s11
	s_cselect_b32 s11, s24, s23
	s_xor_b32 s11, s11, s13
	s_sub_i32 s12, s11, s13
	s_add_i32 s9, s9, s21
	s_mul_i32 s10, s10, s12
	s_add_i32 s9, s9, s8
	s_sub_i32 s8, s9, s10
	s_lshl_b32 s24, s8, 7
	s_lshl_b32 s23, s12, 7
	s_mul_i32 s8, s8, 0xb0000
	s_mul_hi_i32 s9, s24, 0x1600
	s_add_u32 s10, s18, s8
	s_addc_u32 s11, s19, s9
	s_mul_i32 s12, s12, 0xb0000
	s_add_u32 s8, s16, s12
	v_ashrrev_i32_e32 v19, 3, v18
	s_movk_i32 s12, 0xb00
	v_lshlrev_b32_e32 v2, 3, v18
	v_mul_lo_u32 v0, v19, s12
	v_and_b32_e32 v20, 56, v2
	v_bfe_u32 v21, v18, 4, 3
	v_lshlrev_b32_e32 v21, 3, v21
	v_xor_b32_e32 v20, v20, v21
	v_or_b32_e32 v0, v0, v20
	s_mul_hi_i32 s9, s23, 0x1600
	v_add_u32_e32 v6, 0x42000, v0
	s_addc_u32 s9, s17, s9
	v_add_u32_e32 v2, 0x16000, v0
	v_mov_b32_e32 v3, v1
	v_add_u32_e32 v4, 0x2c000, v0
	v_mov_b32_e32 v5, v1
	s_waitcnt vmcnt(0)
	v_lshlrev_b64 v[146:147], 1, v[6:7]
	v_lshl_add_u64 v[6:7], s[8:9], 0, v[146:147]
	v_lshlrev_b64 v[148:149], 1, v[4:5]
	v_lshlrev_b64 v[150:151], 1, v[2:3]
	v_lshlrev_b64 v[152:153], 1, v[0:1]
	v_lshl_add_u64 v[8:9], s[10:11], 0, v[146:147]
	v_lshl_add_u64 v[4:5], s[8:9], 0, v[148:149]
	v_lshl_add_u64 v[10:11], s[10:11], 0, v[148:149]
	v_lshl_add_u64 v[2:3], s[8:9], 0, v[150:151]
	v_lshl_add_u64 v[12:13], s[10:11], 0, v[150:151]
	v_lshl_add_u64 v[14:15], s[8:9], 0, v[152:153]
	v_lshl_add_u64 v[16:17], s[10:11], 0, v[152:153]
	v_readfirstlane_b32 s38, v203
	s_nop 3
	s_lshr_b32 s38, s38, 6
	s_lshl_b32 s38, s38, 10
	v_and_b32_e32 v140, 31, v203
	v_bfe_u32 v141, v203, 5, 1
	v_bfe_u32 v142, v203, 1, 3
	v_xor_b32_e32 v141, v141, v142
	v_lshlrev_b32_e32 v141, 4, v141
	v_lshl_or_b32 v140, v140, 7, v141
	v_lshrrev_b32_e32 v142, 7, v203
	v_lshl_add_u32 v130, v142, 13, v140
	v_bfe_u32 v142, v203, 6, 1
	v_lshl_add_u32 v134, v142, 13, v140
	v_xor_b32_e32 v131, 0x20, v130
	v_xor_b32_e32 v135, 0x20, v134
	v_xor_b32_e32 v132, 0x40, v130
	v_xor_b32_e32 v136, 0x40, v134
	v_xor_b32_e32 v133, 0x60, v130
	v_xor_b32_e32 v137, 0x60, v134
	s_add_u32 m0, s38, 0x0
	s_nop 0
	global_load_lds_dwordx4 v152, s[10:11]
	s_add_u32 m0, s38, 0x4000
	s_nop 0
	global_load_lds_dwordx4 v152, s[8:9]
	s_add_u32 m0, s38, 0x1000
	s_nop 0
	global_load_lds_dwordx4 v150, s[10:11]
	s_add_u32 m0, s38, 0x5000
	s_nop 0
	global_load_lds_dwordx4 v150, s[8:9]
	s_add_u32 m0, s38, 0x2000
	s_nop 0
	global_load_lds_dwordx4 v148, s[10:11]
	s_add_u32 m0, s38, 0x6000
	s_nop 0
	global_load_lds_dwordx4 v148, s[8:9]
	s_add_u32 m0, s38, 0x3000
	s_nop 0
	global_load_lds_dwordx4 v146, s[10:11]
	s_add_u32 m0, s38, 0x7000
	s_nop 0
	global_load_lds_dwordx4 v146, s[8:9]
	s_add_u32 s8, s8, 0x80
	s_addc_u32 s9, s9, 0
	s_add_u32 s10, s10, 0x80
	s_addc_u32 s11, s11, 0
	v_mov_b32_e32 v2, 0
	s_mov_b32 s22, 0
	v_mov_b32_e32 v3, v2
	v_mov_b32_e32 v4, v2
	v_mov_b32_e32 v5, v2
	v_mov_b32_e32 v6, v2
	v_mov_b32_e32 v7, v2
	v_mov_b32_e32 v8, v2
	v_mov_b32_e32 v9, v2
	v_mov_b32_e32 v10, v2
	v_mov_b32_e32 v11, v2
	v_mov_b32_e32 v12, v2
	v_mov_b32_e32 v13, v2
	v_mov_b32_e32 v14, v2
	v_mov_b32_e32 v15, v2
	v_mov_b32_e32 v16, v2
	v_mov_b32_e32 v17, v2
	v_mov_b32_e32 v18, v2
	v_mov_b32_e32 v19, v2
	v_mov_b32_e32 v20, v2
	v_mov_b32_e32 v21, v2
	v_mov_b32_e32 v22, v2
	v_mov_b32_e32 v23, v2
	v_mov_b32_e32 v24, v2
	v_mov_b32_e32 v25, v2
	v_mov_b32_e32 v26, v2
	v_mov_b32_e32 v27, v2
	v_mov_b32_e32 v28, v2
	v_mov_b32_e32 v29, v2
	v_mov_b32_e32 v30, v2
	v_mov_b32_e32 v31, v2
	v_mov_b32_e32 v32, v2
	v_mov_b32_e32 v33, v2
	v_mov_b32_e32 v34, v2
	v_mov_b32_e32 v35, v2
	v_mov_b32_e32 v36, v2
	v_mov_b32_e32 v37, v2
	v_mov_b32_e32 v38, v2
	v_mov_b32_e32 v39, v2
	v_mov_b32_e32 v40, v2
	v_mov_b32_e32 v41, v2
	v_mov_b32_e32 v42, v2
	v_mov_b32_e32 v43, v2
	v_mov_b32_e32 v44, v2
	v_mov_b32_e32 v45, v2
	v_mov_b32_e32 v46, v2
	v_mov_b32_e32 v47, v2
	v_mov_b32_e32 v48, v2
	v_mov_b32_e32 v49, v2
	v_mov_b32_e32 v50, v2
	v_mov_b32_e32 v51, v2
	v_mov_b32_e32 v52, v2
	v_mov_b32_e32 v53, v2
	v_mov_b32_e32 v54, v2
	v_mov_b32_e32 v55, v2
	v_mov_b32_e32 v56, v2
	v_mov_b32_e32 v57, v2
	v_mov_b32_e32 v58, v2
	v_mov_b32_e32 v59, v2
	v_mov_b32_e32 v60, v2
	v_mov_b32_e32 v61, v2
	v_mov_b32_e32 v62, v2
	v_mov_b32_e32 v63, v2
	v_mov_b32_e32 v64, v2
	v_mov_b32_e32 v65, v2
	s_waitcnt vmcnt(0)
	s_barrier
	.p2align 6

.Lf2_nl0:
	s_waitcnt lgkmcnt(6)
	v_mfma_f32_32x32x16_f16 v[50:65], v[66:69], v[74:77], v[50:65]
	ds_read_b128 v[98:101], v132 offset:0
	s_waitcnt lgkmcnt(6)
	v_mfma_f32_32x32x16_f16 v[34:49], v[66:69], v[78:81], v[34:49]
	ds_read_b128 v[106:109], v136 offset:16384
	s_waitcnt lgkmcnt(6)
	v_mfma_f32_32x32x16_f16 v[18:33], v[70:73], v[74:77], v[18:33]
	ds_read_b128 v[110:113], v136 offset:20480
	v_mfma_f32_32x32x16_f16 v[2:17], v[70:73], v[78:81], v[2:17]
	ds_read_b128 v[102:105], v132 offset:4096
	s_waitcnt lgkmcnt(6)
	v_mfma_f32_32x32x16_f16 v[50:65], v[82:85], v[90:93], v[50:65]
	ds_read_b128 v[114:117], v133 offset:0
	s_waitcnt lgkmcnt(6)
	v_mfma_f32_32x32x16_f16 v[34:49], v[82:85], v[94:97], v[34:49]
	ds_read_b128 v[122:125], v137 offset:16384
	s_waitcnt lgkmcnt(6)
	v_mfma_f32_32x32x16_f16 v[18:33], v[86:89], v[90:93], v[18:33]
	ds_read_b128 v[126:129], v137 offset:20480
	v_mfma_f32_32x32x16_f16 v[2:17], v[86:89], v[94:97], v[2:17]
	ds_read_b128 v[118:121], v133 offset:4096
	.p2align 6

.Lf2_nl1:
	s_waitcnt lgkmcnt(6)
	v_mfma_f32_32x32x16_f16 v[50:65], v[66:69], v[74:77], v[50:65]
	ds_read_b128 v[98:101], v132 offset:32768
	s_waitcnt lgkmcnt(6)
	v_mfma_f32_32x32x16_f16 v[34:49], v[66:69], v[78:81], v[34:49]
	ds_read_b128 v[106:109], v136 offset:49152
	s_waitcnt lgkmcnt(6)
	v_mfma_f32_32x32x16_f16 v[18:33], v[70:73], v[74:77], v[18:33]
	ds_read_b128 v[110:113], v136 offset:53248
	v_mfma_f32_32x32x16_f16 v[2:17], v[70:73], v[78:81], v[2:17]
	ds_read_b128 v[102:105], v132 offset:36864
	s_waitcnt lgkmcnt(6)
	v_mfma_f32_32x32x16_f16 v[50:65], v[82:85], v[90:93], v[50:65]
	ds_read_b128 v[114:117], v133 offset:32768
	s_waitcnt lgkmcnt(6)
	v_mfma_f32_32x32x16_f16 v[34:49], v[82:85], v[94:97], v[34:49]
	ds_read_b128 v[122:125], v137 offset:49152
	s_waitcnt lgkmcnt(6)
	v_mfma_f32_32x32x16_f16 v[18:33], v[86:89], v[90:93], v[18:33]
	ds_read_b128 v[126:129], v137 offset:53248
	v_mfma_f32_32x32x16_f16 v[2:17], v[86:89], v[94:97], v[2:17]
	ds_read_b128 v[118:121], v133 offset:36864
	.p2align 6

; DI int TIDX() { int t = threadIdx.x; asm volatile("" : "+v"(t)); return t; }
; #define XCD_LOOP_W(Mt, ntn) const int xcd_ = BIDX() & 7; const int Mx_ = ((Mt) + 7) >> 3; for (int u_ = BIDX() >> 3; u_ < Mx_ * (ntn); u_ += (int)(gridDim.x >> 3))
; template <class BR>
; DI void gemm_tile_w(const h16* __restrict__ A, int lda, const h16* __restrict__ B, int ldb, BR brow, int K, f32x16 (&acc)[4][2], h16* sm) {
;   const int tid = TIDX(), lane = tid & 63, w = tid >> 6, wm = w >> 1, wn = w & 1, r = lane & 31, hh = lane >> 5;
;   const unsigned ao = (unsigned)(tid >> 2) * (unsigned)lda + (unsigned)(tid & 3) * 8u;
;   const unsigned bo0 = (unsigned)brow(tid >> 2) * (unsigned)ldb + (unsigned)(tid & 3) * 8u;
;   const unsigned bo1 = (unsigned)brow((tid >> 2) + 64) * (unsigned)ldb + (unsigned)(tid & 3) * 8u;
;   const h16* ag = A;
;   const h16* bg = B;
;   u32x4 ra0[4], rb0[2], ra1[4], rb1[2];
; #pragma unroll
;   for (int i = 0; i < 4; ++i) ra0[i] = *(const u32x4*)(ag + (ao + (unsigned)i * 64u * (unsigned)lda));
;   rb0[0] = *(const u32x4*)(bg + bo0);
;   rb0[1] = *(const u32x4*)(bg + bo1);
;   ag += 32; bg += 32;
; #pragma unroll
;   for (int i = 0; i < 4; ++i) ra1[i] = *(const u32x4*)(ag + (ao + (unsigned)i * 64u * (unsigned)lda));
;   rb1[0] = *(const u32x4*)(bg + bo0);
;   rb1[1] = *(const u32x4*)(bg + bo1);
;   const int nk = K >> 5;
;   const int wofs = (tid >> 2) * LS2 + (tid & 3) * 8;
; DI void phase_ffn1(const P& p, int l, int hf, char* smem) {
;     ...
;   XCD_LOOP_W(Mt, 44) {
;     int mt_, nt_;
;     tile_map(u_, Mx_, 44, xcd_, mt_, nt_);
;     if (mt_ >= Mt) continue;
;     const int m0 = mt0 * 128 + mt_ * 256, c0 = nt_ * 64;
;     f32x16 acc[4][2];
;     zero_acc_w(acc);
;     gemm_tile_w(h2 + (size_t)m0 * 1024, 1024, W, 1024,
;                 [&](int rr) { const int q = rr & 63; return ((q >> 5) ? 2816 : 0) + c0 + (rr >> 6) * 32 + (q & 31); }, 1024, acc, (h16*)smem);
.LBB0_71:
	s_mul_hi_i32 s12, s22, 0x2e8ba2e9
	s_lshr_b32 s13, s12, 31
	s_ashr_i32 s12, s12, 6
	s_add_i32 s12, s12, s13
	s_lshl_b32 s14, s12, 3
	s_sub_i32 s13, s21, s14
	s_min_i32 s15, s13, 8
	s_abs_i32 s13, s15
	v_cvt_f32_u32_e32 v0, s13
	s_sub_i32 s18, 0, s13
	s_mulk_i32 s12, 0xfea0
	s_add_i32 s12, s12, s22
	v_rcp_iflag_f32_e32 v0, v0
	s_abs_i32 s16, s12
	s_xor_b32 s17, s12, s15
	s_ashr_i32 s17, s17, 31
	v_mul_f32_e32 v0, 0x4f7ffffe, v0
	v_cvt_u32_f32_e32 v0, v0
	s_nop 0
	v_readfirstlane_b32 s19, v0
	s_mul_i32 s18, s18, s19
	s_mul_hi_u32 s18, s19, s18
	s_add_i32 s19, s19, s18
	s_mul_hi_u32 s18, s16, s19
	s_mul_i32 s19, s18, s13
	s_sub_i32 s16, s16, s19
	s_add_i32 s26, s18, 1
	s_sub_i32 s19, s16, s13
	s_cmp_ge_u32 s16, s13
	s_cselect_b32 s18, s26, s18
	s_cselect_b32 s16, s19, s16
	s_add_i32 s19, s18, 1
	s_cmp_ge_u32 s16, s13
	s_cselect_b32 s13, s19, s18
	s_xor_b32 s13, s13, s17
	s_sub_i32 s13, s13, s17
	s_add_i32 s14, s14, s38
	s_mul_i32 s15, s15, s13
	s_add_i32 s14, s14, s12
	s_sub_i32 s12, s14, s15
	s_cmp_ge_i32 s12, s20
	s_cbranch_scc1 .LBB0_70
	v_mov_b32_e32 v18, v203
	s_lshl_b32 s26, s13, 6
	s_lshl_b32 s12, s12, 8
	v_ashrrev_i32_e32 v19, 2, v18
	v_bfe_i32 v2, v18, 7, 1
	v_and_b32_e32 v2, 0xb00, v2
	v_lshrrev_b32_e32 v3, 3, v18
	v_and_or_b32 v4, v19, 31, s26
	v_and_b32_e32 v3, 0x3fffe0, v3
	v_add_u32_e32 v2, v2, v4
	v_add_u32_e32 v10, v2, v3
	v_add_u32_e32 v3, 64, v19
	s_ashr_i32 s13, s12, 31
	v_lshlrev_b32_e32 v0, 3, v18
	v_lshrrev_b32_e32 v3, 1, v3
	s_lshl_b64 s[14:15], s[12:13], 11
	v_and_b32_e32 v20, 24, v0
	v_bfe_u32 v21, v18, 4, 2
	v_lshlrev_b32_e32 v21, 3, v21
	v_xor_b32_e32 v20, v20, v21
	v_and_b32_e32 v3, 0x3fffe0, v3
	s_add_u32 s14, s24, s14
	v_add_u32_e32 v11, v2, v3
	v_lshl_or_b32 v210, v10, 10, v20
	v_mov_b32_e32 v211, v1
	s_addc_u32 s15, s25, s15
	v_lshl_or_b32 v0, v19, 10, v20
	v_lshl_or_b32 v212, v11, 10, v20
	v_lshlrev_b64 v[10:11], 1, v[210:211]
	v_mov_b32_e32 v213, v1
	v_lshl_add_u64 v[2:3], v[0:1], 1, s[14:15]
	v_add_u32_e32 v204, 0x10000, v0
	v_mov_b32_e32 v205, v1
	v_add_u32_e32 v206, 0x20000, v0
	v_mov_b32_e32 v207, v1
	v_add_u32_e32 v208, 0x30000, v0
	v_mov_b32_e32 v209, v1
	v_lshl_add_u64 v[12:13], s[6:7], 0, v[10:11]
	v_lshlrev_b64 v[14:15], 1, v[212:213]
	v_lshl_add_u64 v[4:5], v[204:205], 1, s[14:15]
	v_lshl_add_u64 v[6:7], v[206:207], 1, s[14:15]
	v_lshl_add_u64 v[8:9], v[208:209], 1, s[14:15]
	v_lshl_add_u64 v[16:17], s[6:7], 0, v[14:15]
	v_readfirstlane_b32 s18, v203
	s_nop 3
	s_lshr_b32 s18, s18, 6
	s_lshl_b32 s18, s18, 10
	v_and_b32_e32 v136, 31, v203
	v_bfe_u32 v137, v203, 5, 1
	v_bfe_u32 v138, v203, 2, 2
	v_xor_b32_e32 v137, v137, v138
	v_lshlrev_b32_e32 v137, 4, v137
	v_lshl_or_b32 v136, v136, 6, v137
	v_lshrrev_b32_e32 v138, 7, v203
	v_lshl_add_u32 v130, v138, 13, v136
	v_bfe_u32 v138, v203, 6, 1
	v_lshl_add_u32 v132, v138, 12, v136
	v_xor_b32_e32 v131, 32, v130
	v_xor_b32_e32 v133, 32, v132
	v_lshlrev_b32_e32 v139, 1, v0
	v_lshlrev_b32_e32 v140, 1, v204
	v_lshlrev_b32_e32 v141, 1, v206
	v_lshlrev_b32_e32 v142, 1, v208
	v_lshlrev_b32_e32 v143, 1, v210
	v_lshlrev_b32_e32 v144, 1, v212
	s_mov_b64 s[16:17], s[6:7]
	s_add_u32 m0, s18, 0x0
	s_nop 0
	global_load_lds_dwordx4 v139, s[14:15]
	s_add_u32 m0, s18, 0x1000
	s_nop 0
	global_load_lds_dwordx4 v140, s[14:15]
	s_add_u32 m0, s18, 0x2000
	s_nop 0
	global_load_lds_dwordx4 v141, s[14:15]
	s_add_u32 m0, s18, 0x3000
	s_nop 0
	global_load_lds_dwordx4 v142, s[14:15]
	s_add_u32 m0, s18, 0x4000
	s_nop 0
	global_load_lds_dwordx4 v143, s[16:17]
	s_add_u32 m0, s18, 0x5000
	s_nop 0
	global_load_lds_dwordx4 v144, s[16:17]
	s_add_u32 s14, s14, 64
	s_addc_u32 s15, s15, 0
	s_add_u32 s16, s16, 64
	s_addc_u32 s17, s17, 0
	v_mov_b32_e32 v2, 0
	s_mov_b32 s13, 0
	v_mov_b32_e32 v3, v2
	v_mov_b32_e32 v4, v2
	v_mov_b32_e32 v5, v2
	v_mov_b32_e32 v6, v2
	v_mov_b32_e32 v7, v2
	v_mov_b32_e32 v8, v2
	v_mov_b32_e32 v9, v2
	v_mov_b32_e32 v10, v2
	v_mov_b32_e32 v11, v2
	v_mov_b32_e32 v12, v2
	v_mov_b32_e32 v13, v2
	v_mov_b32_e32 v14, v2
	v_mov_b32_e32 v15, v2
	v_mov_b32_e32 v16, v2
	v_mov_b32_e32 v17, v2
	v_mov_b32_e32 v18, v2
	v_mov_b32_e32 v19, v2
	v_mov_b32_e32 v20, v2
	v_mov_b32_e32 v21, v2
	v_mov_b32_e32 v22, v2
	v_mov_b32_e32 v23, v2
	v_mov_b32_e32 v24, v2
	v_mov_b32_e32 v25, v2
	v_mov_b32_e32 v26, v2
	v_mov_b32_e32 v27, v2
	v_mov_b32_e32 v28, v2
	v_mov_b32_e32 v29, v2
	v_mov_b32_e32 v30, v2
	v_mov_b32_e32 v31, v2
	v_mov_b32_e32 v32, v2
	v_mov_b32_e32 v33, v2
	v_mov_b32_e32 v34, v2
	v_mov_b32_e32 v35, v2
	v_mov_b32_e32 v36, v2
	v_mov_b32_e32 v37, v2
	v_mov_b32_e32 v38, v2
	v_mov_b32_e32 v39, v2
	v_mov_b32_e32 v40, v2
	v_mov_b32_e32 v41, v2
	v_mov_b32_e32 v42, v2
	v_mov_b32_e32 v43, v2
	v_mov_b32_e32 v44, v2
	v_mov_b32_e32 v45, v2
	v_mov_b32_e32 v46, v2
	v_mov_b32_e32 v47, v2
	v_mov_b32_e32 v48, v2
	v_mov_b32_e32 v49, v2
	s_waitcnt vmcnt(15)
	v_mov_b32_e32 v50, v2
	v_mov_b32_e32 v51, v2
	v_mov_b32_e32 v52, v2
	v_mov_b32_e32 v53, v2
	s_waitcnt vmcnt(14)
	v_mov_b32_e32 v54, v2
	v_mov_b32_e32 v55, v2
	v_mov_b32_e32 v56, v2
	v_mov_b32_e32 v57, v2
	s_waitcnt vmcnt(13)
	v_mov_b32_e32 v58, v2
	v_mov_b32_e32 v59, v2
	v_mov_b32_e32 v60, v2
	v_mov_b32_e32 v61, v2
	s_waitcnt vmcnt(12)
	v_mov_b32_e32 v62, v2
	v_mov_b32_e32 v63, v2
	v_mov_b32_e32 v64, v2
	v_mov_b32_e32 v65, v2
	v_mov_b32_e32 v66, v2
	v_mov_b32_e32 v67, v2
	v_mov_b32_e32 v68, v2
	v_mov_b32_e32 v69, v2
	v_mov_b32_e32 v70, v2
	v_mov_b32_e32 v71, v2
	v_mov_b32_e32 v72, v2
	v_mov_b32_e32 v73, v2
	v_mov_b32_e32 v74, v2
	v_mov_b32_e32 v75, v2
	v_mov_b32_e32 v76, v2
	v_mov_b32_e32 v77, v2
	v_mov_b32_e32 v78, v2
	v_mov_b32_e32 v79, v2
	v_mov_b32_e32 v80, v2
	v_mov_b32_e32 v81, v2
	v_mov_b32_e32 v82, v2
	v_mov_b32_e32 v83, v2
	v_mov_b32_e32 v84, v2
	v_mov_b32_e32 v85, v2
	v_mov_b32_e32 v86, v2
	v_mov_b32_e32 v87, v2
	v_mov_b32_e32 v88, v2
	v_mov_b32_e32 v89, v2
	v_mov_b32_e32 v90, v2
	v_mov_b32_e32 v91, v2
	v_mov_b32_e32 v92, v2
	v_mov_b32_e32 v93, v2
	v_mov_b32_e32 v94, v2
	v_mov_b32_e32 v95, v2
	v_mov_b32_e32 v96, v2
	v_mov_b32_e32 v97, v2
	v_mov_b32_e32 v98, v2
	v_mov_b32_e32 v99, v2
	v_mov_b32_e32 v100, v2
	v_mov_b32_e32 v101, v2
	v_mov_b32_e32 v102, v2
	v_mov_b32_e32 v103, v2
	v_mov_b32_e32 v104, v2
	v_mov_b32_e32 v105, v2
	v_mov_b32_e32 v106, v2
	v_mov_b32_e32 v107, v2
	v_mov_b32_e32 v108, v2
	v_mov_b32_e32 v109, v2
	v_mov_b32_e32 v110, v2
	v_mov_b32_e32 v111, v2
	v_mov_b32_e32 v112, v2
	v_mov_b32_e32 v113, v2
	v_mov_b32_e32 v114, v2
	v_mov_b32_e32 v115, v2
	v_mov_b32_e32 v116, v2
	v_mov_b32_e32 v117, v2
	v_mov_b32_e32 v118, v2
	v_mov_b32_e32 v119, v2
	v_mov_b32_e32 v120, v2
	v_mov_b32_e32 v121, v2
	v_mov_b32_e32 v122, v2
	v_mov_b32_e32 v123, v2
	v_mov_b32_e32 v124, v2
	v_mov_b32_e32 v125, v2
	v_mov_b32_e32 v126, v2
	v_mov_b32_e32 v127, v2
	v_mov_b32_e32 v128, v2
	v_mov_b32_e32 v129, v2
	s_waitcnt vmcnt(0)
	s_barrier
	.p2align 6

.Lfg_nl0:
	s_waitcnt lgkmcnt(4)
	v_mfma_f32_32x32x16_f16 v[114:129], v[178:181], v[194:197], v[114:129]
	ds_read_b128 v[216:219], v131 offset:0
	s_waitcnt lgkmcnt(4)
	v_mfma_f32_32x32x16_f16 v[98:113], v[178:181], v[198:201], v[98:113]
	ds_read_b128 v[234:237], v133 offset:16384
	s_waitcnt lgkmcnt(4)
	v_mfma_f32_32x32x16_f16 v[82:97], v[182:185], v[194:197], v[82:97]
	ds_read_b128 v[240:243], v133 offset:18432
	v_mfma_f32_32x32x16_f16 v[66:81], v[182:185], v[198:201], v[66:81]
	ds_read_b128 v[220:223], v131 offset:2048
	s_waitcnt lgkmcnt(5)
	v_mfma_f32_32x32x16_f16 v[50:65], v[186:189], v[194:197], v[50:65]
	ds_read_b128 v[226:229], v131 offset:4096
	v_mfma_f32_32x32x16_f16 v[34:49], v[186:189], v[198:201], v[34:49]
	ds_read_b128 v[230:233], v131 offset:6144
	s_waitcnt lgkmcnt(6)
	v_mfma_f32_32x32x16_f16 v[18:33], v[190:193], v[194:197], v[18:33]
	v_mfma_f32_32x32x16_f16 v[2:17], v[190:193], v[198:201], v[2:17]
	.p2align 6

.Lfg_nl1:
	s_waitcnt lgkmcnt(4)
	v_mfma_f32_32x32x16_f16 v[114:129], v[178:181], v[194:197], v[114:129]
	ds_read_b128 v[216:219], v131 offset:24576
	s_waitcnt lgkmcnt(4)
	v_mfma_f32_32x32x16_f16 v[98:113], v[178:181], v[198:201], v[98:113]
	ds_read_b128 v[234:237], v133 offset:40960
	s_waitcnt lgkmcnt(4)
	v_mfma_f32_32x32x16_f16 v[82:97], v[182:185], v[194:197], v[82:97]
	ds_read_b128 v[240:243], v133 offset:43008
	v_mfma_f32_32x32x16_f16 v[66:81], v[182:185], v[198:201], v[66:81]
	ds_read_b128 v[220:223], v131 offset:26624
	s_waitcnt lgkmcnt(5)
	v_mfma_f32_32x32x16_f16 v[50:65], v[186:189], v[194:197], v[50:65]
	ds_read_b128 v[226:229], v131 offset:28672
	v_mfma_f32_32x32x16_f16 v[34:49], v[186:189], v[198:201], v[34:49]
	ds_read_b128 v[230:233], v131 offset:30720
	s_waitcnt lgkmcnt(6)
	v_mfma_f32_32x32x16_f16 v[18:33], v[190:193], v[194:197], v[18:33]
	v_mfma_f32_32x32x16_f16 v[2:17], v[190:193], v[198:201], v[2:17]
	.p2align 6

; DI int TIDX() { int t = threadIdx.x; asm volatile("" : "+v"(t)); return t; }
; #define XCD_LOOP(Mx, ntn) const int xcd_ = BIDX() & 7; for (int u_ = BIDX() >> 3; u_ < (Mx) * (ntn); u_ += (int)(gridDim.x >> 3))
; DI void gemm_tile_deep(const h16* __restrict__ A, int lda, const h16* __restrict__ B, int ldb, int K, f32x16 (&acc)[2][2], h16* sm) {
;   const int tid = TIDX(), lane = tid & 63, w = tid >> 6, wm = w >> 1, wn = w & 1, r = lane & 31, hh = lane >> 5;
;   const unsigned ao = (unsigned)(tid >> 3) * (unsigned)lda + (unsigned)(tid & 7) * 8u;
;   const unsigned bo = (unsigned)(tid >> 3) * (unsigned)ldb + (unsigned)(tid & 7) * 8u;
;   const h16* ag = A;
;   const h16* bg = B;
;   u32x4 ra0[4], rb0[4], ra1[4], rb1[4];
; #pragma unroll
;   for (int i = 0; i < 4; ++i) {
;     ra0[i] = *(const u32x4*)(ag + (ao + (unsigned)i * 32u * (unsigned)lda));
;     rb0[i] = *(const u32x4*)(bg + (bo + (unsigned)i * 32u * (unsigned)ldb));
;   }
;   ag += 64; bg += 64;
; #pragma unroll
;   for (int i = 0; i < 4; ++i) {
;     ra1[i] = *(const u32x4*)(ag + (ao + (unsigned)i * 32u * (unsigned)lda));
;     rb1[i] = *(const u32x4*)(bg + (bo + (unsigned)i * 32u * (unsigned)ldb));
;   }
;   const int nk = K >> 6;
;   const int wofs = (tid >> 3) * LSTR + (tid & 7) * 8;
; DI void phase_gemm_plain(const h16* A, int lda, const h16* Bt, int K, h16* C, int ldc, int mt0, int mt1, int ntn, char* smem) {
;     ...
;   XCD_LOOP(Mx, ntn) {
;     int mt_, nt_;
;     tile_map(u_, Mx, ntn, xcd_, mt_, nt_);
;     const int m0 = (mt0 + mt_) * 128, n0 = nt_ * 128;
;     f32x16 acc[2][2];
;     zero_acc(acc);
;     gemm_tile_deep(A + (size_t)m0 * lda, lda, Bt + (size_t)n0 * K, K, K, acc, (h16*)smem);
.LBB0_91:
	s_ashr_i32 s4, s15, 31
	s_lshr_b32 s4, s4, 26
	s_add_i32 s4, s15, s4
	s_ashr_i32 s5, s4, 6
	s_lshl_b32 s5, s5, 3
	s_sub_i32 s6, s20, s5
	s_min_i32 s6, s6, 8
	s_abs_i32 s7, s6
	v_cvt_f32_u32_e32 v0, s7
	s_sub_i32 s10, 0, s7
	s_andn2_b32 s4, s4, 63
	s_sub_i32 s4, s15, s4
	v_rcp_iflag_f32_e32 v0, v0
	s_abs_i32 s8, s4
	s_xor_b32 s9, s4, s6
	s_ashr_i32 s9, s9, 31
	v_mul_f32_e32 v0, 0x4f7ffffe, v0
	v_cvt_u32_f32_e32 v0, v0
	v_mov_b32_e32 v18, v203
	v_mov_b32_e32 v7, v1
	v_readfirstlane_b32 s11, v0
	s_mul_i32 s10, s10, s11
	s_mul_hi_u32 s10, s11, s10
	s_add_i32 s11, s11, s10
	s_mul_hi_u32 s10, s8, s11
	s_mul_i32 s11, s10, s7
	s_sub_i32 s8, s8, s11
	s_add_i32 s12, s10, 1
	s_sub_i32 s11, s8, s7
	s_cmp_ge_u32 s8, s7
	s_cselect_b32 s10, s12, s10
	s_cselect_b32 s8, s11, s8
	s_add_i32 s11, s10, 1
	s_cmp_ge_u32 s8, s7
	s_cselect_b32 s7, s11, s10
	s_xor_b32 s7, s7, s9
	s_sub_i32 s7, s7, s9
	s_add_i32 s5, s5, s21
	s_mul_i32 s6, s6, s7
	s_add_i32 s5, s5, s4
	s_sub_i32 s4, s5, s6
	s_lshl_b32 s6, s4, 7
	s_lshl_b32 s4, s7, 7
	s_ashr_i32 s7, s6, 31
	s_lshl_b64 s[8:9], s[6:7], 11
	s_add_u32 s10, s16, s8
	v_lshlrev_b32_e32 v0, 3, v18
	s_addc_u32 s11, s17, s9
	s_ashr_i32 s5, s4, 31
	v_ashrrev_i32_e32 v19, 3, v18
	v_and_b32_e32 v20, 56, v0
	v_bfe_u32 v21, v18, 4, 3
	v_lshlrev_b32_e32 v21, 3, v21
	v_xor_b32_e32 v20, v20, v21
	s_lshl_b64 s[8:9], s[4:5], 11
	v_lshl_or_b32 v0, v19, 10, v20
	s_add_u32 s8, s18, s8
	v_add_u32_e32 v6, 0x18000, v0
	s_addc_u32 s9, s19, s9
	v_add_u32_e32 v2, 0x8000, v0
	v_mov_b32_e32 v3, v1
	v_add_u32_e32 v4, 0x10000, v0
	v_mov_b32_e32 v5, v1
	s_waitcnt vmcnt(0)
	v_lshlrev_b64 v[146:147], 1, v[6:7]
	v_lshl_add_u64 v[6:7], s[8:9], 0, v[146:147]
	v_lshlrev_b64 v[148:149], 1, v[4:5]
	v_lshlrev_b64 v[150:151], 1, v[2:3]
	v_lshlrev_b64 v[152:153], 1, v[0:1]
	v_lshl_add_u64 v[8:9], s[10:11], 0, v[146:147]
	v_lshl_add_u64 v[4:5], s[8:9], 0, v[148:149]
	v_lshl_add_u64 v[10:11], s[10:11], 0, v[148:149]
	v_lshl_add_u64 v[2:3], s[8:9], 0, v[150:151]
	v_lshl_add_u64 v[12:13], s[10:11], 0, v[150:151]
	v_lshl_add_u64 v[14:15], s[8:9], 0, v[152:153]
	v_lshl_add_u64 v[16:17], s[10:11], 0, v[152:153]
	v_readfirstlane_b32 s38, v203
	s_nop 3
	s_lshr_b32 s38, s38, 6
	s_lshl_b32 s38, s38, 10
	v_and_b32_e32 v140, 31, v203
	v_bfe_u32 v141, v203, 5, 1
	v_bfe_u32 v142, v203, 1, 3
	v_xor_b32_e32 v141, v141, v142
	v_lshlrev_b32_e32 v141, 4, v141
	v_lshl_or_b32 v140, v140, 7, v141
	v_lshrrev_b32_e32 v142, 7, v203
	v_lshl_add_u32 v130, v142, 13, v140
	v_bfe_u32 v142, v203, 6, 1
	v_lshl_add_u32 v134, v142, 13, v140
	v_xor_b32_e32 v131, 0x20, v130
	v_xor_b32_e32 v135, 0x20, v134
	v_xor_b32_e32 v132, 0x40, v130
	v_xor_b32_e32 v136, 0x40, v134
	v_xor_b32_e32 v133, 0x60, v130
	v_xor_b32_e32 v137, 0x60, v134
	s_add_u32 m0, s38, 0x0
	s_nop 0
	global_load_lds_dwordx4 v152, s[10:11]
	s_add_u32 m0, s38, 0x4000
	s_nop 0
	global_load_lds_dwordx4 v152, s[8:9]
	s_add_u32 m0, s38, 0x1000
	s_nop 0
	global_load_lds_dwordx4 v150, s[10:11]
	s_add_u32 m0, s38, 0x5000
	s_nop 0
	global_load_lds_dwordx4 v150, s[8:9]
	s_add_u32 m0, s38, 0x2000
	s_nop 0
	global_load_lds_dwordx4 v148, s[10:11]
	s_add_u32 m0, s38, 0x6000
	s_nop 0
	global_load_lds_dwordx4 v148, s[8:9]
	s_add_u32 m0, s38, 0x3000
	s_nop 0
	global_load_lds_dwordx4 v146, s[10:11]
	s_add_u32 m0, s38, 0x7000
	s_nop 0
	global_load_lds_dwordx4 v146, s[8:9]
	s_add_u32 s8, s8, 0x80
	s_addc_u32 s9, s9, 0
	s_add_u32 s10, s10, 0x80
	s_addc_u32 s11, s11, 0
	v_mov_b32_e32 v2, 0
	s_mov_b32 s22, 0
	v_mov_b32_e32 v3, v2
	v_mov_b32_e32 v4, v2
	v_mov_b32_e32 v5, v2
	v_mov_b32_e32 v6, v2
	v_mov_b32_e32 v7, v2
	v_mov_b32_e32 v8, v2
	v_mov_b32_e32 v9, v2
	v_mov_b32_e32 v10, v2
	v_mov_b32_e32 v11, v2
	v_mov_b32_e32 v12, v2
	v_mov_b32_e32 v13, v2
	v_mov_b32_e32 v14, v2
	v_mov_b32_e32 v15, v2
	v_mov_b32_e32 v16, v2
	v_mov_b32_e32 v17, v2
	v_mov_b32_e32 v18, v2
	v_mov_b32_e32 v19, v2
	v_mov_b32_e32 v20, v2
	v_mov_b32_e32 v21, v2
	v_mov_b32_e32 v22, v2
	v_mov_b32_e32 v23, v2
	v_mov_b32_e32 v24, v2
	v_mov_b32_e32 v25, v2
	v_mov_b32_e32 v26, v2
	v_mov_b32_e32 v27, v2
	v_mov_b32_e32 v28, v2
	v_mov_b32_e32 v29, v2
	v_mov_b32_e32 v30, v2
	v_mov_b32_e32 v31, v2
	v_mov_b32_e32 v32, v2
	v_mov_b32_e32 v33, v2
	v_mov_b32_e32 v34, v2
	v_mov_b32_e32 v35, v2
	v_mov_b32_e32 v36, v2
	v_mov_b32_e32 v37, v2
	v_mov_b32_e32 v38, v2
	v_mov_b32_e32 v39, v2
	v_mov_b32_e32 v40, v2
	v_mov_b32_e32 v41, v2
	v_mov_b32_e32 v42, v2
	v_mov_b32_e32 v43, v2
	v_mov_b32_e32 v44, v2
	v_mov_b32_e32 v45, v2
	v_mov_b32_e32 v46, v2
	v_mov_b32_e32 v47, v2
	v_mov_b32_e32 v48, v2
	v_mov_b32_e32 v49, v2
	v_mov_b32_e32 v50, v2
	v_mov_b32_e32 v51, v2
	v_mov_b32_e32 v52, v2
	v_mov_b32_e32 v53, v2
	v_mov_b32_e32 v54, v2
	v_mov_b32_e32 v55, v2
	v_mov_b32_e32 v56, v2
	v_mov_b32_e32 v57, v2
	v_mov_b32_e32 v58, v2
	v_mov_b32_e32 v59, v2
	v_mov_b32_e32 v60, v2
	v_mov_b32_e32 v61, v2
	v_mov_b32_e32 v62, v2
	v_mov_b32_e32 v63, v2
	v_mov_b32_e32 v64, v2
	v_mov_b32_e32 v65, v2
	s_waitcnt vmcnt(0)
	s_barrier
	.p2align 6

; DI int TIDX() { int t = threadIdx.x; asm volatile("" : "+v"(t)); return t; }
; #define XCD_LOOP_W(Mt, ntn) const int xcd_ = BIDX() & 7; const int Mx_ = ((Mt) + 7) >> 3; for (int u_ = BIDX() >> 3; u_ < Mx_ * (ntn); u_ += (int)(gridDim.x >> 3))
; template <class BR>
; DI void gemm_tile_w(const h16* __restrict__ A, int lda, const h16* __restrict__ B, int ldb, BR brow, int K, f32x16 (&acc)[4][2], h16* sm) {
;   const int tid = TIDX(), lane = tid & 63, w = tid >> 6, wm = w >> 1, wn = w & 1, r = lane & 31, hh = lane >> 5;
;   const unsigned ao = (unsigned)(tid >> 2) * (unsigned)lda + (unsigned)(tid & 3) * 8u;
;   const unsigned bo0 = (unsigned)brow(tid >> 2) * (unsigned)ldb + (unsigned)(tid & 3) * 8u;
;   const unsigned bo1 = (unsigned)brow((tid >> 2) + 64) * (unsigned)ldb + (unsigned)(tid & 3) * 8u;
;   const h16* ag = A;
;   const h16* bg = B;
;   u32x4 ra0[4], rb0[2], ra1[4], rb1[2];
; #pragma unroll
;   for (int i = 0; i < 4; ++i) ra0[i] = *(const u32x4*)(ag + (ao + (unsigned)i * 64u * (unsigned)lda));
;   rb0[0] = *(const u32x4*)(bg + bo0);
;   rb0[1] = *(const u32x4*)(bg + bo1);
;   ag += 32; bg += 32;
; #pragma unroll
;   for (int i = 0; i < 4; ++i) ra1[i] = *(const u32x4*)(ag + (ao + (unsigned)i * 64u * (unsigned)lda));
;   rb1[0] = *(const u32x4*)(bg + bo0);
;   rb1[1] = *(const u32x4*)(bg + bo1);
;   const int nk = K >> 5;
;   const int wofs = (tid >> 2) * LS2 + (tid & 3) * 8;
; DI void phase_proj(const P& p, int l, char* smem) {
;     ...
;   XCD_LOOP_W(136, 27) {
;     int mt_, nt_;
;     tile_map(u_, Mx_, 27, xcd_, mt_, nt_);
;     if (mt_ >= 136) continue;
;     const int m0 = mt_ * 256, n0 = nt_ * 128;
;     f32x16 acc[4][2];
;     zero_acc_w(acc);
;     gemm_tile_w(hbuf + (size_t)m0 * 1024, 1024, W, 1024, [&](int rr) { return n0 + rr; }, 1024, acc, (h16*)smem);
.LBB0_693:
	s_mul_hi_i32 s0, s36, 0x4bda12f7
	s_lshr_b32 s1, s0, 31
	s_ashr_i32 s0, s0, 6
	s_add_i32 s0, s0, s1
	s_lshl_b32 s4, s0, 3
	s_sub_i32 s1, 17, s4
	s_min_u32 s5, s1, 8
	v_cvt_f32_ubyte0_e32 v0, s5
	v_rcp_iflag_f32_e32 v0, v0
	s_sub_i32 s7, 0, s5
	s_mulk_i32 s0, 0xff28
	s_add_i32 s0, s0, s36
	v_mul_f32_e32 v0, 0x4f7ffffe, v0
	v_cvt_u32_f32_e32 v0, v0
	s_abs_i32 s6, s0
	s_ashr_i32 s1, s0, 31
	v_readfirstlane_b32 s8, v0
	s_mul_i32 s7, s7, s8
	s_mul_hi_u32 s7, s8, s7
	s_add_i32 s8, s8, s7
	s_mul_hi_u32 s7, s6, s8
	s_mul_i32 s8, s7, s5
	s_sub_i32 s6, s6, s8
	s_add_i32 s8, s7, 1
	s_sub_i32 s9, s6, s5
	s_cmp_ge_u32 s6, s5
	s_cselect_b32 s7, s8, s7
	s_cselect_b32 s6, s9, s6
	s_add_i32 s8, s7, 1
	s_cmp_ge_u32 s6, s5
	s_cselect_b32 s6, s8, s7
	s_xor_b32 s6, s6, s1
	s_sub_i32 s1, s6, s1
	s_add_i32 s4, s4, s72
	s_mul_i32 s5, s5, s1
	s_add_i32 s4, s4, s0
	s_sub_i32 s0, s4, s5
	s_cmpk_gt_i32 s0, 0x87
	s_cbranch_scc1 .LBB0_692
	s_lshl_b32 s0, s0, 8
	s_lshl_b32 s10, s1, 7
	s_ashr_i32 s1, s0, 31
	v_mov_b32_e32 v14, v203
	s_lshl_b64 s[4:5], s[0:1], 11
	s_add_u32 s4, s69, s4
	v_ashrrev_i32_e32 v15, 2, v14
	v_lshlrev_b32_e32 v0, 3, v14
	v_and_b32_e32 v16, 24, v0
	v_bfe_u32 v17, v14, 4, 2
	v_lshlrev_b32_e32 v17, 3, v17
	v_xor_b32_e32 v16, v16, v17
	v_add_u32_e32 v10, s10, v15
	s_addc_u32 s5, s24, s5
	v_lshl_or_b32 v0, v15, 10, v16
	v_lshl_or_b32 v210, v10, 10, v16
	v_lshl_add_u64 v[2:3], v[0:1], 1, s[4:5]
	v_add_u32_e32 v204, 0x10000, v0
	v_mov_b32_e32 v205, v1
	v_add_u32_e32 v206, 0x20000, v0
	v_mov_b32_e32 v207, v1
	v_add_u32_e32 v208, 0x30000, v0
	v_mov_b32_e32 v209, v1
	v_add_u32_e32 v212, 0x10000, v210
	v_mov_b32_e32 v211, v1
	s_mov_b64 s[6:7], s[54:55]
	v_mov_b32_e32 v213, v1
	v_lshl_add_u64 v[4:5], v[204:205], 1, s[4:5]
	v_lshl_add_u64 v[6:7], v[206:207], 1, s[4:5]
	v_lshl_add_u64 v[8:9], v[208:209], 1, s[4:5]
	v_lshl_add_u64 v[10:11], v[210:211], 1, s[6:7]
	v_lshl_add_u64 v[12:13], v[212:213], 1, s[6:7]
	v_readfirstlane_b32 s18, v203
	s_nop 3
	s_lshr_b32 s18, s18, 6
	s_lshl_b32 s18, s18, 10
	v_and_b32_e32 v136, 31, v203
	v_bfe_u32 v137, v203, 5, 1
	v_bfe_u32 v138, v203, 2, 2
	v_xor_b32_e32 v137, v137, v138
	v_lshlrev_b32_e32 v137, 4, v137
	v_lshl_or_b32 v136, v136, 6, v137
	v_lshrrev_b32_e32 v138, 7, v203
	v_lshl_add_u32 v130, v138, 13, v136
	v_bfe_u32 v138, v203, 6, 1
	v_lshl_add_u32 v132, v138, 12, v136
	v_xor_b32_e32 v131, 32, v130
	v_xor_b32_e32 v133, 32, v132
	v_lshlrev_b32_e32 v139, 1, v0
	v_lshlrev_b32_e32 v140, 1, v204
	v_lshlrev_b32_e32 v141, 1, v206
	v_lshlrev_b32_e32 v142, 1, v208
	v_lshlrev_b32_e32 v143, 1, v210
	v_lshlrev_b32_e32 v144, 1, v212
	s_add_u32 m0, s18, 0x0
	s_nop 0
	global_load_lds_dwordx4 v139, s[4:5]
	s_add_u32 m0, s18, 0x1000
	s_nop 0
	global_load_lds_dwordx4 v140, s[4:5]
	s_add_u32 m0, s18, 0x2000
	s_nop 0
	global_load_lds_dwordx4 v141, s[4:5]
	s_add_u32 m0, s18, 0x3000
	s_nop 0
	global_load_lds_dwordx4 v142, s[4:5]
	s_add_u32 m0, s18, 0x4000
	s_nop 0
	global_load_lds_dwordx4 v143, s[6:7]
	s_add_u32 m0, s18, 0x5000
	s_nop 0
	global_load_lds_dwordx4 v144, s[6:7]
	s_add_u32 s4, s4, 64
	s_addc_u32 s5, s5, 0
	s_add_u32 s6, s6, 64
	s_addc_u32 s7, s7, 0
	v_mov_b32_e32 v114, 0
	s_mov_b32 s1, 0
	v_mov_b32_e32 v115, v114
	v_mov_b32_e32 v116, v114
	s_waitcnt vmcnt(14)
	v_mov_b32_e32 v117, v114
	v_mov_b32_e32 v118, v114
	v_mov_b32_e32 v119, v114
	s_waitcnt vmcnt(13)
	v_mov_b32_e32 v120, v114
	v_mov_b32_e32 v121, v114
	v_mov_b32_e32 v122, v114
	s_waitcnt vmcnt(12)
	v_mov_b32_e32 v123, v114
	v_mov_b32_e32 v124, v114
	v_mov_b32_e32 v125, v114
	v_mov_b32_e32 v126, v114
	v_mov_b32_e32 v127, v114
	v_mov_b32_e32 v128, v114
	v_mov_b32_e32 v129, v114
	v_mov_b32_e32 v98, v114
	v_mov_b32_e32 v99, v114
	v_mov_b32_e32 v100, v114
	v_mov_b32_e32 v101, v114
	v_mov_b32_e32 v102, v114
	v_mov_b32_e32 v103, v114
	v_mov_b32_e32 v104, v114
	v_mov_b32_e32 v105, v114
	v_mov_b32_e32 v106, v114
	v_mov_b32_e32 v107, v114
	v_mov_b32_e32 v108, v114
	v_mov_b32_e32 v109, v114
	v_mov_b32_e32 v110, v114
	v_mov_b32_e32 v111, v114
	v_mov_b32_e32 v112, v114
	v_mov_b32_e32 v113, v114
	v_mov_b32_e32 v82, v114
	v_mov_b32_e32 v83, v114
	v_mov_b32_e32 v84, v114
	v_mov_b32_e32 v85, v114
	v_mov_b32_e32 v86, v114
	v_mov_b32_e32 v87, v114
	v_mov_b32_e32 v88, v114
	v_mov_b32_e32 v89, v114
	v_mov_b32_e32 v90, v114
	v_mov_b32_e32 v91, v114
	v_mov_b32_e32 v92, v114
	v_mov_b32_e32 v93, v114
	v_mov_b32_e32 v94, v114
	v_mov_b32_e32 v95, v114
	v_mov_b32_e32 v96, v114
	v_mov_b32_e32 v97, v114
	v_mov_b32_e32 v66, v114
	v_mov_b32_e32 v67, v114
	v_mov_b32_e32 v68, v114
	v_mov_b32_e32 v69, v114
	v_mov_b32_e32 v70, v114
	v_mov_b32_e32 v71, v114
	v_mov_b32_e32 v72, v114
	v_mov_b32_e32 v73, v114
	v_mov_b32_e32 v74, v114
	v_mov_b32_e32 v75, v114
	v_mov_b32_e32 v76, v114
	v_mov_b32_e32 v77, v114
	v_mov_b32_e32 v78, v114
	v_mov_b32_e32 v79, v114
	v_mov_b32_e32 v80, v114
	v_mov_b32_e32 v81, v114
	v_mov_b32_e32 v50, v114
	v_mov_b32_e32 v51, v114
	v_mov_b32_e32 v52, v114
	v_mov_b32_e32 v53, v114
	v_mov_b32_e32 v54, v114
	v_mov_b32_e32 v55, v114
	v_mov_b32_e32 v56, v114
	v_mov_b32_e32 v57, v114
	v_mov_b32_e32 v58, v114
	v_mov_b32_e32 v59, v114
	v_mov_b32_e32 v60, v114
	v_mov_b32_e32 v61, v114
	v_mov_b32_e32 v62, v114
	v_mov_b32_e32 v63, v114
	v_mov_b32_e32 v64, v114
	v_mov_b32_e32 v65, v114
	v_mov_b32_e32 v34, v114
	v_mov_b32_e32 v35, v114
	v_mov_b32_e32 v36, v114
	v_mov_b32_e32 v37, v114
	v_mov_b32_e32 v38, v114
	v_mov_b32_e32 v39, v114
	v_mov_b32_e32 v40, v114
	v_mov_b32_e32 v41, v114
	v_mov_b32_e32 v42, v114
	v_mov_b32_e32 v43, v114
	v_mov_b32_e32 v44, v114
	v_mov_b32_e32 v45, v114
	v_mov_b32_e32 v46, v114
	v_mov_b32_e32 v47, v114
	v_mov_b32_e32 v48, v114
	v_mov_b32_e32 v49, v114
	v_mov_b32_e32 v18, v114
	v_mov_b32_e32 v19, v114
	v_mov_b32_e32 v20, v114
	v_mov_b32_e32 v21, v114
	v_mov_b32_e32 v22, v114
	v_mov_b32_e32 v23, v114
	v_mov_b32_e32 v24, v114
	v_mov_b32_e32 v25, v114
	v_mov_b32_e32 v26, v114
	v_mov_b32_e32 v27, v114
	v_mov_b32_e32 v28, v114
	v_mov_b32_e32 v29, v114
	v_mov_b32_e32 v30, v114
	v_mov_b32_e32 v31, v114
	v_mov_b32_e32 v32, v114
	v_mov_b32_e32 v33, v114
	v_mov_b32_e32 v2, v114
	v_mov_b32_e32 v3, v114
	v_mov_b32_e32 v4, v114
	v_mov_b32_e32 v5, v114
	v_mov_b32_e32 v6, v114
	v_mov_b32_e32 v7, v114
	v_mov_b32_e32 v8, v114
	v_mov_b32_e32 v9, v114
	v_mov_b32_e32 v10, v114
	v_mov_b32_e32 v11, v114
	v_mov_b32_e32 v12, v114
	v_mov_b32_e32 v13, v114
	v_mov_b32_e32 v14, v114
	v_mov_b32_e32 v15, v114
	v_mov_b32_e32 v16, v114
	v_mov_b32_e32 v17, v114
	s_waitcnt vmcnt(0)
	s_barrier
	.p2align 6
